# block-id permutation variant: k -> ((k&15)<<2)|(k>>4)
# speedup vs baseline: 1.0048x; 1.0048x over previous
.Lrole_done:
	s_lshl_b32 s98, s98, 1
	s_or_b32 s99, s99, s98
	s_lshl_b32 s100, s100, 2
	s_or_b32 s101, s99, s100
	v_readlane_b32 s98, v252, 0
	s_lshr_b32 s98, s98, 3
	s_and_b32 s98, s98, 0xff
	s_lshl_b32 s98, s98, 8
	s_or_b32 s101, s101, s98
	v_readlane_b32 s98, v252, 0
	s_lshr_b32 s99, s98, 3
	s_and_b32 s98, s98, 7
	s_and_b32 s100, s99, 15
	s_lshl_b32 s100, s100, 2
	s_lshr_b32 s99, s99, 4
	s_or_b32 s99, s99, s100
	s_lshl_b32 s99, s99, 3
	s_or_b32 s98, s98, s99
	s_nop 0
	v_writelane_b32 v252, s98, 0
	s_load_dwordx2 s[52:53], s[0:1], 0x210
	s_waitcnt lgkmcnt(0)
	s_cmp_ge_i32 s52, s53
	s_cbranch_scc1 .Lend_near
	s_load_dwordx2 s[22:23], s[0:1], 0x1a8
	s_load_dwordx16 s[56:71], s[0:1], 0x0
	s_load_dwordx16 s[36:51], s[0:1], 0x40
	s_load_dwordx16 s[4:19], s[0:1], 0x80
	v_lshrrev_b32_e32 v1, 20, v0
	v_lshrrev_b32_e32 v0, 10, v0
	v_or_b32_e32 v0, v0, v1
	s_mov_b32 s97, 0
	s_waitcnt lgkmcnt(0)
	v_writelane_b32 v252, s4, 5
	s_movk_i32 s55, 0x4000
	v_mov_b32_e32 v2, 0
	v_writelane_b32 v252, s5, 6
	v_writelane_b32 v252, s6, 7
	v_writelane_b32 v252, s7, 8
	v_writelane_b32 v252, s8, 9
	v_writelane_b32 v252, s9, 10
	v_writelane_b32 v252, s10, 11
	v_writelane_b32 v252, s11, 12
	v_writelane_b32 v252, s12, 13
	v_writelane_b32 v252, s13, 14
	v_writelane_b32 v252, s14, 15
	v_writelane_b32 v252, s15, 16
	v_writelane_b32 v252, s16, 17
	v_writelane_b32 v252, s17, 18
	v_writelane_b32 v252, s18, 19
	v_writelane_b32 v252, s19, 20
	s_load_dwordx16 s[4:19], s[0:1], 0xc0
	s_mov_b32 s28, 0x10000
	v_mov_b32_e32 v198, 0x358637bd
	s_movk_i32 s96, 0x43ff
	s_mov_b32 s29, 0x20000
	s_waitcnt lgkmcnt(0)
	v_writelane_b32 v252, s4, 21
	v_mov_b32_e32 v199, 0x10000
	s_movk_i32 s33, 0x110
	v_writelane_b32 v252, s5, 22
	v_writelane_b32 v252, s6, 23
	v_writelane_b32 v252, s7, 24
	v_writelane_b32 v252, s8, 25
	v_writelane_b32 v252, s9, 26
	v_writelane_b32 v252, s10, 27
	v_writelane_b32 v252, s11, 28
	v_writelane_b32 v252, s12, 29
	v_writelane_b32 v252, s13, 30
	v_writelane_b32 v252, s14, 31
	v_writelane_b32 v252, s15, 32
	v_writelane_b32 v252, s16, 33
	v_writelane_b32 v252, s17, 34
	v_writelane_b32 v252, s18, 35
	v_writelane_b32 v252, s19, 36
	s_load_dwordx16 s[4:19], s[0:1], 0x100
	v_mov_b32_e32 v201, 0x3ecc95a3
	v_mov_b64_e32 v[212:213], 0xe00
	v_mov_b64_e32 v[196:197], 0x3600
	v_mov_b32_e32 v204, 0x7f800000
	s_waitcnt lgkmcnt(0)
	v_writelane_b32 v252, s4, 37
	v_mov_b32_e32 v206, 0x41b17218
	v_mov_b32_e32 v136, 0x3f317218
	v_writelane_b32 v252, s5, 38
	v_writelane_b32 v252, s6, 39
	v_writelane_b32 v252, s7, 40
	v_writelane_b32 v252, s8, 41
	v_writelane_b32 v252, s9, 42
	v_writelane_b32 v252, s10, 43
	v_writelane_b32 v252, s11, 44
	v_writelane_b32 v252, s12, 45
	v_writelane_b32 v252, s13, 46
	v_writelane_b32 v252, s14, 47
	v_writelane_b32 v252, s15, 48
	v_writelane_b32 v252, s16, 49
	v_writelane_b32 v252, s17, 50
	v_writelane_b32 v252, s18, 51
	v_writelane_b32 v252, s19, 52
	s_load_dwordx16 s[72:87], s[0:1], 0x140
	s_load_dwordx16 s[4:19], s[0:1], 0x1b0
	v_mov_b32_e32 v203, 0x7fc00000
	v_mov_b32_e32 v195, 0xff800000
	v_mov_b32_e32 v205, 0xe400
	v_mov_b32_e32 v200, 0x9f00
	s_waitcnt lgkmcnt(0)
	v_writelane_b32 v252, s4, 53
	v_mov_b32_e32 v207, 0x42800000
	s_nop 0
	v_writelane_b32 v252, s5, 54
	v_writelane_b32 v252, s6, 55
	v_writelane_b32 v252, s7, 56
	v_writelane_b32 v253, s15, 0
	v_writelane_b32 v252, s8, 57
	v_writelane_b32 v253, s16, 1
	v_writelane_b32 v252, s9, 58
	v_writelane_b32 v253, s17, 2
	v_writelane_b32 v252, s10, 59
	v_writelane_b32 v253, s18, 3
	v_writelane_b32 v252, s11, 60
	v_writelane_b32 v253, s19, 4
	s_load_dwordx8 s[4:11], s[0:1], 0x1f0
	s_add_u32 s0, s0, 0x218
	s_addc_u32 s1, s1, 0
	v_writelane_b32 v252, s12, 61
	v_writelane_b32 v252, s13, 62
	s_waitcnt lgkmcnt(0)
	v_writelane_b32 v253, s4, 5
	v_writelane_b32 v252, s14, 63
	s_nop 0
	v_writelane_b32 v253, s5, 6
	v_writelane_b32 v253, s6, 7
	v_writelane_b32 v253, s7, 8
	v_writelane_b32 v253, s8, 9
	v_writelane_b32 v253, s9, 10
	v_writelane_b32 v253, s10, 11
	v_writelane_b32 v253, s11, 12
	v_writelane_b32 v253, s0, 13
	s_nop 1
	v_writelane_b32 v253, s1, 14
	s_add_u32 s0, s88, 0x200
	s_addc_u32 s1, s89, 0
	v_writelane_b32 v253, s0, 15
	s_nop 1
	v_writelane_b32 v253, s1, 16
	s_add_u32 s0, s88, 0x1000
	s_addc_u32 s1, s89, 0
	v_writelane_b32 v253, s0, 17
	s_nop 1
	v_writelane_b32 v253, s1, 18
	s_add_u32 s0, s88, 0x1100
	s_addc_u32 s1, s89, 0
	v_writelane_b32 v253, s0, 19
	s_nop 1
	v_writelane_b32 v253, s1, 20
	s_add_u32 s0, s88, 0x1200
	s_addc_u32 s1, s89, 0
	v_writelane_b32 v253, s0, 21
	s_nop 1
	v_writelane_b32 v253, s1, 22
	s_add_u32 s0, s88, 0x1300
	s_addc_u32 s1, s89, 0
	v_writelane_b32 v253, s0, 23
	s_cmp_eq_u32 s20, 15
	s_nop 0
	v_writelane_b32 v253, s1, 24
	s_cselect_b64 s[0:1], -1, 0
	v_writelane_b32 v253, s0, 25
	s_cmp_eq_u32 s20, 14
	s_nop 0
	v_writelane_b32 v253, s1, 26
	s_cselect_b64 s[0:1], -1, 0
	v_writelane_b32 v253, s0, 27
	s_cmp_eq_u32 s20, 13
	s_nop 0
	v_writelane_b32 v253, s1, 28
	s_cselect_b64 s[0:1], -1, 0
	v_writelane_b32 v253, s0, 29
	s_cmp_eq_u32 s20, 12
	s_nop 0
	v_writelane_b32 v253, s1, 30
	s_cselect_b64 s[0:1], -1, 0
	v_writelane_b32 v253, s0, 31
	s_cmp_eq_u32 s20, 11
	s_nop 0
	v_writelane_b32 v253, s1, 32
	s_cselect_b64 s[0:1], -1, 0
	v_writelane_b32 v253, s0, 33
	s_cmp_eq_u32 s20, 10
	s_nop 0
	v_writelane_b32 v253, s1, 34
	s_cselect_b64 s[0:1], -1, 0
	v_writelane_b32 v253, s0, 35
	s_cmp_eq_u32 s20, 9
	s_nop 0
	v_writelane_b32 v253, s1, 36
	s_cselect_b64 s[0:1], -1, 0
	v_writelane_b32 v253, s0, 37
	s_cmp_eq_u32 s20, 8
	s_nop 0
	v_writelane_b32 v253, s1, 38
	s_cselect_b64 s[0:1], -1, 0
	v_writelane_b32 v253, s0, 39
	s_cmp_eq_u32 s20, 7
	s_nop 0
	v_writelane_b32 v253, s1, 40
	s_cselect_b64 s[0:1], -1, 0
	v_writelane_b32 v253, s0, 41
	s_cmp_eq_u32 s20, 6
	s_nop 0
	v_writelane_b32 v253, s1, 42
	s_cselect_b64 s[0:1], -1, 0
	v_writelane_b32 v253, s0, 43
	s_cmp_eq_u32 s20, 5
	s_nop 0
	v_writelane_b32 v253, s1, 44
	s_cselect_b64 s[0:1], -1, 0
	v_writelane_b32 v253, s0, 45
	s_cmp_eq_u32 s20, 4
	s_nop 0
	v_writelane_b32 v253, s1, 46
	s_cselect_b64 s[0:1], -1, 0
	v_writelane_b32 v253, s0, 47
	s_cmp_eq_u32 s20, 3
	s_nop 0
	v_writelane_b32 v253, s1, 48
	s_cselect_b64 s[0:1], -1, 0
	v_writelane_b32 v253, s0, 49
	s_cmp_eq_u32 s20, 2
	s_nop 0
	v_writelane_b32 v253, s1, 50
	s_cselect_b64 s[0:1], -1, 0
	v_writelane_b32 v253, s0, 51
	s_cmp_eq_u32 s20, 1
	s_nop 0
	v_writelane_b32 v253, s1, 52
	s_cselect_b64 s[0:1], -1, 0
	v_writelane_b32 v253, s0, 53
	s_cmp_eq_u32 s20, 0
	s_nop 0
	v_writelane_b32 v253, s1, 54
	s_cselect_b64 s[0:1], -1, 0
	v_writelane_b32 v253, s0, 55
	s_nop 1
	v_writelane_b32 v253, s1, 56
	s_lshl_b32 s0, s20, 8
	s_add_u32 s0, s88, s0
	s_addc_u32 s1, s89, 0
	s_add_u32 s2, s0, 0x1400
	s_addc_u32 s3, s1, 0
	v_writelane_b32 v253, s2, 57
	s_add_u32 s0, s0, 0x2400
	s_addc_u32 s1, s1, 0
	v_writelane_b32 v253, s3, 58
	v_writelane_b32 v253, s0, 59
	v_readlane_b32 s3, v252, 0
	s_nop 0
	v_writelane_b32 v253, s1, 60
	s_add_u32 s0, s88, 0x3400
	s_addc_u32 s1, s89, 0
	v_writelane_b32 v253, s0, 61
	s_nop 1
	v_writelane_b32 v253, s1, 62
	s_add_u32 s0, s88, 0x3500
	s_addc_u32 s1, s89, 0
	v_writelane_b32 v253, s0, 63
	s_cmp_lt_i32 s53, 0
	s_nop 0
	v_writelane_b32 v254, s1, 0
	s_cselect_b64 s[0:1], -1, 0
	v_writelane_b32 v254, s0, 1
	s_nop 1
	v_writelane_b32 v254, s1, 2
	s_movk_i32 s0, 0x3ff
	v_and_or_b32 v0, v0, s0, v194
	v_cmp_eq_u32_e64 s[0:1], 0, v0
	s_nop 1
	v_writelane_b32 v254, s0, 3
	s_nop 1
	v_writelane_b32 v254, s1, 4
	s_lshl_b32 s0, s3, 2
	v_writelane_b32 v254, s0, 5
	s_add_u32 s0, s42, 0x1000
	v_writelane_b32 v254, s36, 6
	s_addc_u32 s1, s43, 0
	s_cmp_lg_u64 s[84:85], 0
	v_writelane_b32 v254, s37, 7
	v_writelane_b32 v254, s38, 8
	v_writelane_b32 v254, s39, 9
	v_writelane_b32 v254, s40, 10
	v_writelane_b32 v254, s41, 11
	v_writelane_b32 v254, s42, 12
	v_writelane_b32 v254, s43, 13
	v_writelane_b32 v254, s44, 14
	v_writelane_b32 v254, s45, 15
	v_writelane_b32 v254, s46, 16
	v_writelane_b32 v254, s47, 17
	v_writelane_b32 v254, s48, 18
	v_writelane_b32 v254, s49, 19
	v_writelane_b32 v254, s50, 20
	v_writelane_b32 v254, s51, 21
	v_writelane_b32 v254, s0, 22
	s_mov_b64 s[36:37], 0x800
	s_nop 0
	v_writelane_b32 v254, s1, 23
	s_cselect_b64 s[0:1], -1, 0
	v_writelane_b32 v254, s0, 24
	s_cmpk_lt_i32 s3, 0x1560
	s_nop 0
	v_writelane_b32 v254, s1, 25
	s_cselect_b64 s[0:1], -1, 0
	v_writelane_b32 v254, s0, 26
	s_cmp_lg_u64 s[76:77], 0
	s_nop 0
	v_writelane_b32 v254, s1, 27
	s_cselect_b64 s[0:1], -1, 0
	v_writelane_b32 v254, s0, 28
	s_and_b32 s4, s3, 7
	s_lshl_b32 s2, s3, 4
	v_writelane_b32 v254, s1, 29
	s_lshr_b32 s0, s3, 3
	s_lshl_b32 s1, s4, 6
	v_writelane_b32 v254, s0, 30
	s_add_i32 s0, s1, s0
	v_writelane_b32 v254, s1, 31
	s_lshl_b32 s0, s0, 4
	s_and_b32 s2, s2, 0x380
	s_and_b32 s1, s0, 0xfffffc00
	v_writelane_b32 v254, s2, 32
	s_and_b32 s0, s0, 0x380
	v_writelane_b32 v254, s0, 33
	s_lshl_b32 s0, s3, 1
	s_and_b32 s0, s0, 0x7fffff80
	s_or_b32 s1, s1, s2
	s_addk_i32 s0, 0x4000
	v_writelane_b32 v254, s0, 34
	s_add_i32 s54, s1, 0x2000
	s_lshl_b32 s0, s4, 22
	v_writelane_b32 v254, s1, 35
	s_add_u32 s0, s80, s0
	v_writelane_b32 v254, s4, 36
	s_addc_u32 s1, s81, 0
	v_writelane_b32 v254, s0, 37
	s_nop 1
	v_writelane_b32 v254, s1, 38
	s_add_i32 s1, s22, -1
	s_mul_i32 s0, s1, 0x60
	v_writelane_b32 v254, s0, 39
	s_mul_i32 s0, s1, 0xa0
	v_writelane_b32 v254, s0, 40
	s_ashr_i32 s0, s1, 31
	v_writelane_b32 v254, s0, 41
	v_writelane_b32 v254, s22, 42
	s_sub_i32 s0, 1, s22
	s_max_i32 s0, s1, s0
	v_cvt_f32_u32_e32 v0, s0
	v_writelane_b32 v254, s23, 43
	v_writelane_b32 v254, s1, 44
	v_writelane_b32 v254, s0, 45
	v_rcp_iflag_f32_e32 v0, v0
	s_sub_i32 s0, 0, s0
	v_mul_f32_e32 v0, 0x4f7ffffe, v0
	v_cvt_u32_f32_e32 v0, v0
	s_nop 0
	v_readfirstlane_b32 s1, v0
	s_mul_i32 s0, s0, s1
	s_mul_hi_u32 s0, s1, s0
	s_add_i32 s0, s1, s0
	v_writelane_b32 v254, s0, 46
	s_add_u32 s0, s78, 64
	s_addc_u32 s1, s79, 0
	v_writelane_b32 v254, s0, 47
	v_mbcnt_lo_u32_b32 v0, -1, 0
	s_nop 0
	v_writelane_b32 v254, s1, 48
	v_readlane_b32 s0, v252, 1
	v_readlane_b32 s1, v252, 2
	s_add_u32 s2, s0, 0x100
	s_addc_u32 s3, s1, 0
	v_writelane_b32 v254, s2, 49
	v_mbcnt_hi_u32_b32 v202, -1, v0
	s_nop 0
	v_writelane_b32 v254, s3, 50
	s_add_u32 s2, s0, 0x140
	s_addc_u32 s3, s1, 0
	v_writelane_b32 v254, s2, 51
	s_nop 1
	v_writelane_b32 v254, s3, 52
	s_add_u32 s2, s0, 0x180
	s_addc_u32 s3, s1, 0
	v_writelane_b32 v254, s2, 53
	s_add_u32 s0, s0, 0x1c0
	s_addc_u32 s1, s1, 0
	v_writelane_b32 v254, s3, 54
	v_writelane_b32 v254, s0, 55
	s_mov_b32 s2, s52
	s_nop 0
	v_writelane_b32 v254, s1, 56
	s_add_u32 s0, s78, 0x2c00
	s_addc_u32 s1, s79, 0
	v_writelane_b32 v254, s0, 57
	s_nop 1
	v_writelane_b32 v254, s1, 58
	v_writelane_b32 v254, s54, 59
	v_writelane_b32 v254, s52, 60
	s_nop 1
	v_writelane_b32 v254, s53, 61
	s_branch .LBB0_9
